# v38 + V tile fetched two tiles ahead in the diff loops (three V buffers), end-of-step wait leaves this step's V pieces in flight
# speedup vs baseline: 1.0081x; 1.0081x over previous
; #define ATT_BAR() asm volatile("s_waitcnt lgkmcnt(0)\n\ts_barrier" ::: "memory")
; #define ATT_BAR() asm volatile("s_waitcnt vmcnt(0) lgkmcnt(0)\n\ts_barrier" ::: "memory")
; template <int DQK>
; __device__ __forceinline__ void attn_pass4(LAS unsigned char* lds, const bf16* Qp, int qpitch, const bf16* Kp, int kpitch, const bf16* Vp, int vpitch, int q0, f32x16 (&o)[4], float (&rl)[16]) {
;     ...
;     ATT_DMA(0, 0, 0); ATT_BAR();
.LBB0_619:
	s_add_u32 s70, s54, 0x20000
	s_addc_u32 s71, s55, 0
	v_lshl_add_u64 v[36:37], s[70:71], 0, v[172:173]
	s_lshl_b32 s8, s3, 10
	s_add_i32 s8, s8, 0x9800
	s_mov_b32 m0, s8
	s_nop 0
	global_load_lds_dwordx4 v[36:37], off
	v_lshl_add_u64 v[36:37], s[70:71], 0, v[174:175]
	s_lshl_b32 s8, s2, 10
	s_add_i32 s8, s8, 0x9800
	s_mov_b32 m0, s8
	s_nop 0
	global_load_lds_dwordx4 v[36:37], off
	s_cmp_gt_i32 s3, 3
	s_cbranch_scc1 .Lv1pre_0
	v_lshl_add_u64 v[36:37], s[70:71], 0, v[178:179]
	s_lshl_b32 s8, s3, 10
	s_add_i32 s8, s8, 0xd800
	s_mov_b32 m0, s8
	s_nop 0
	global_load_lds_dwordx4 v[36:37], off

; template <int DQK>
; __device__ __forceinline__ void attn_pass4(LAS unsigned char* lds, const bf16* Qp, int qpitch, const bf16* Kp, int kpitch, const bf16* Vp, int vpitch, int q0, f32x16 (&o)[4], float (&rl)[16]) {
;     ...
;         for (int t = 0; t < NT; ++t) {
;             const int vnext = ATT_VNEXT(vcur);
;             if (t + 1 < NT) ATT_DMA(t + 1, (t + 1) & 1, vnext);
.LBB0_624:
	s_add_i32 s32, s72, 2
	s_cmp_ge_u32 s32, s31
	s_cbranch_scc1 .Lskip_v2_0
	s_add_i32 s73, s35, 1
	s_cmp_lg_u32 s35, 2
	s_cselect_b32 s73, s73, 0
	s_mul_i32 s73, s73, 0x5000
	s_add_i32 s73, s26, s73
	s_mov_b32 m0, s73
	s_add_u32 s74, s70, 0x4020000
	s_addc_u32 s75, s71, 0
	global_load_lds_dwordx4 v172, s[74:75]
	s_add_i32 m0, s73, 0x2000
	v_readfirstlane_b32 s32, v242
	global_load_lds_dwordx4 v174, s[74:75]
	s_cmpk_gt_u32 s32, 0xff
	s_cbranch_scc1 .Lskip_v2_0
	s_add_i32 m0, s73, 0x4000
	v_lshl_add_u64 v[114:115], s[74:75], 0, v[178:179]
	global_load_lds_dwordx4 v[114:115], off

; #define ATT_BAR() asm volatile("s_waitcnt lgkmcnt(0)\n\ts_barrier" ::: "memory")
; #define ATT_BAR() asm volatile("s_waitcnt vmcnt(0) lgkmcnt(0)\n\ts_barrier" ::: "memory")
; template <int DQK>
; __device__ __forceinline__ void attn_pass4(LAS unsigned char* lds, const bf16* Qp, int qpitch, const bf16* Kp, int kpitch, const bf16* Vp, int vpitch, int q0, f32x16 (&o)[4], float (&rl)[16]) {
;     ...
;             ATT_BAR();
.LBB0_638:
	s_add_i32 s18, s18, 64
	s_add_u32 s70, s70, 0x20000
	s_addc_u32 s71, s71, 0
	s_mov_b32 s24, s35
	s_mov_b32 s72, s25
	s_add_i32 s32, s25, 1
	s_cmp_lt_u32 s32, s31
	s_cbranch_scc0 .Lvw0_0
	s_waitcnt vmcnt(2) lgkmcnt(0)
	s_branch .Lvw1_0

; template <int DQK>
; __device__ __forceinline__ void attn_pass4(LAS unsigned char* lds, const bf16* Qp, int qpitch, const bf16* Kp, int kpitch, const bf16* Vp, int vpitch, int q0, f32x16 (&o)[4], float (&rl)[16]) {
;     ...
;         for (int t = 0; t < NT; ++t) {
.Lvw1_0:
	s_cmp_eq_u32 s31, s25
	s_barrier
	s_cbranch_scc1 .LBB0_641
	s_branch .LBB0_621

; #define ATT_BAR() asm volatile("s_waitcnt lgkmcnt(0)\n\ts_barrier" ::: "memory")
; #define ATT_BAR() asm volatile("s_waitcnt vmcnt(0) lgkmcnt(0)\n\ts_barrier" ::: "memory")
; template <int DQK>
; __device__ __forceinline__ void attn_pass4(LAS unsigned char* lds, const bf16* Qp, int qpitch, const bf16* Kp, int kpitch, const bf16* Vp, int vpitch, int q0, f32x16 (&o)[4], float (&rl)[16]) {
;     ...
;     ATT_DMA(0, 0, 0); ATT_BAR();
.LBB0_819:
	s_add_u32 s70, s54, 0x20000
	s_addc_u32 s71, s55, 0
	v_lshl_add_u64 v[36:37], s[70:71], 0, v[172:173]
	s_lshl_b32 s8, s80, 10
	s_add_i32 s8, s8, 0x9800
	s_mov_b32 m0, s8
	s_nop 0
	global_load_lds_dwordx4 v[36:37], off
	v_lshl_add_u64 v[36:37], s[70:71], 0, v[174:175]
	s_lshl_b32 s8, s2, 10
	s_add_i32 s8, s8, 0x9800
	s_mov_b32 m0, s8
	s_nop 0
	global_load_lds_dwordx4 v[36:37], off
	s_cmp_gt_i32 s80, 3
	s_cbranch_scc1 .Lv1pre_1
	v_lshl_add_u64 v[36:37], s[70:71], 0, v[178:179]
	s_lshl_b32 s8, s80, 10
	s_add_i32 s8, s8, 0xd800
	s_mov_b32 m0, s8
	s_nop 0
	global_load_lds_dwordx4 v[36:37], off

; template <int DQK>
; __device__ __forceinline__ void attn_pass4(LAS unsigned char* lds, const bf16* Qp, int qpitch, const bf16* Kp, int kpitch, const bf16* Vp, int vpitch, int q0, f32x16 (&o)[4], float (&rl)[16]) {
;     ...
;         for (int t = 0; t < NT; ++t) {
;             const int vnext = ATT_VNEXT(vcur);
;             if (t + 1 < NT) ATT_DMA(t + 1, (t + 1) & 1, vnext);
.LBB0_824:
	s_add_i32 s32, s72, 2
	s_cmp_ge_u32 s32, s31
	s_cbranch_scc1 .Lskip_v2_1
	s_add_i32 s73, s24, 1
	s_cmp_lg_u32 s24, 2
	s_cselect_b32 s73, s73, 0
	s_mul_i32 s73, s73, 0x5000
	s_add_i32 s73, s5, s73
	s_mov_b32 m0, s73
	s_add_u32 s74, s70, 0x401ff80
	s_addc_u32 s75, s71, 0
	global_load_lds_dwordx4 v172, s[74:75]
	s_add_i32 m0, s73, 0x2000
	v_readfirstlane_b32 s32, v242
	global_load_lds_dwordx4 v174, s[74:75]
	s_cmpk_gt_u32 s32, 0xff
	s_cbranch_scc1 .Lskip_v2_1
	s_add_i32 m0, s73, 0x4000
	v_lshl_add_u64 v[114:115], s[74:75], 0, v[178:179]
	global_load_lds_dwordx4 v[114:115], off

; #define ATT_BAR() asm volatile("s_waitcnt lgkmcnt(0)\n\ts_barrier" ::: "memory")
; #define ATT_BAR() asm volatile("s_waitcnt vmcnt(0) lgkmcnt(0)\n\ts_barrier" ::: "memory")
; template <int DQK>
; __device__ __forceinline__ void attn_pass4(LAS unsigned char* lds, const bf16* Qp, int qpitch, const bf16* Kp, int kpitch, const bf16* Vp, int vpitch, int q0, f32x16 (&o)[4], float (&rl)[16]) {
;     ...
;             ATT_BAR();
.LBB0_838:
	s_add_i32 s18, s18, 64
	s_add_u32 s70, s70, 0x20000
	s_addc_u32 s71, s71, 0
	s_mov_b32 s72, s25
	s_add_i32 s32, s25, 1
	s_cmp_lt_u32 s32, s31
	s_cbranch_scc0 .Lvw0_1
	s_waitcnt vmcnt(2) lgkmcnt(0)
	s_branch .Lvw1_1

; template <int DQK>
; __device__ __forceinline__ void attn_pass4(LAS unsigned char* lds, const bf16* Qp, int qpitch, const bf16* Kp, int kpitch, const bf16* Vp, int vpitch, int q0, f32x16 (&o)[4], float (&rl)[16]) {
;     ...
;         for (int t = 0; t < NT; ++t) {
.Lvw1_1:
	s_cmp_eq_u32 s31, s25
	s_barrier
	s_cbranch_scc1 .LBB0_841
	s_mov_b32 s35, s24
	s_branch .LBB0_821
